# prologue rms-norm row loop: next prompt row's loads issued EXEC-masked right after the current row's data arrives (software prefetch)
# speedup vs baseline: 1.0045x; 1.0045x over previous
.LBB0_236:
	v_readlane_b32 s12, v255, 18
	v_readlane_b32 s13, v255, 19
	s_andn2_b64 vcc, exec, s[12:13]
	s_cbranch_vccnz .LBB0_241
	v_and_b32_e32 v0, 64, v4
	v_add_u32_e32 v0, 64, v0
	v_xor_b32_e32 v1, 1, v4
	v_cmp_lt_i32_e32 vcc, v1, v0
	v_readlane_b32 s66, v255, 30
	v_readlane_b32 s68, v255, 28
	v_cndmask_b32_e32 v1, v4, v1, vcc
	v_lshlrev_b32_e32 v16, 2, v1
	v_xor_b32_e32 v1, 2, v4
	v_cmp_lt_i32_e32 vcc, v1, v0
	v_readlane_b32 s67, v255, 31
	v_readlane_b32 s69, v255, 29
	v_cndmask_b32_e32 v1, v4, v1, vcc
	v_lshlrev_b32_e32 v17, 2, v1
	v_xor_b32_e32 v1, 4, v4
	v_cmp_lt_i32_e32 vcc, v1, v0
	s_nop 1
	v_cndmask_b32_e32 v1, v4, v1, vcc
	v_lshlrev_b32_e32 v18, 2, v1
	v_xor_b32_e32 v1, 8, v4
	v_cmp_lt_i32_e32 vcc, v1, v0
	s_nop 1
	v_cndmask_b32_e32 v1, v4, v1, vcc
	v_lshlrev_b32_e32 v19, 2, v1
	v_xor_b32_e32 v1, 16, v4
	v_cmp_lt_i32_e32 vcc, v1, v0
	s_nop 1
	v_cndmask_b32_e32 v1, v4, v1, vcc
	v_lshlrev_b32_e32 v20, 2, v1
	v_xor_b32_e32 v1, 32, v4
	v_cmp_lt_i32_e32 vcc, v1, v0
	s_nop 1
	v_cndmask_b32_e32 v0, v4, v1, vcc
	v_lshlrev_b32_e32 v21, 2, v0
	s_mov_b32 s57, 0
	s_branch .LBB0_239
.LBB0_238:
	global_load_dwordx4 v[8:11], v189, s[70:71]
	global_load_dwordx4 v[4:7], v189, s[70:71] offset:1024
	global_load_dwordx4 v[0:3], v189, s[70:71] offset:3072
	global_load_dwordx4 v[12:15], v189, s[70:71] offset:2048
	s_lshl_b64 s[12:13], s[12:13], 11
	s_add_u32 s68, s68, s92
	s_addc_u32 s69, s69, s93
	s_add_u32 s66, s66, s42
	s_addc_u32 s67, s67, s43
	s_cmpk_gt_i32 s68, 0x41ff
	s_waitcnt vmcnt(3)
	v_pk_mul_f32 v[22:23], v[10:11], v[10:11]
	v_pk_mul_f32 v[24:25], v[8:9], v[8:9]
	s_waitcnt vmcnt(2)
	v_pk_mul_f32 v[26:27], v[6:7], v[6:7]
	v_pk_mul_f32 v[28:29], v[4:5], v[4:5]
	v_pk_mov_b32 v[34:35], v[24:25], v[22:23] op_sel:[1,0]
	v_mov_b32_e32 v25, v23
	v_pk_mov_b32 v[22:23], v[28:29], v[26:27] op_sel:[1,0]
	v_mov_b32_e32 v29, v27
	s_waitcnt vmcnt(1)
	v_mul_f32_e32 v33, v0, v0
	s_waitcnt vmcnt(0)
	s_mov_b64 exec, s[52:53]
	global_load_dwordx4 v[220:223], v189, s[66:67]
	global_load_dwordx4 v[224:227], v189, s[66:67] offset:1024
	global_load_dwordx4 v[228:231], v189, s[66:67] offset:3072
	global_load_dwordx4 v[232:235], v189, s[66:67] offset:2048
	s_mov_b64 exec, -1
	v_mul_f32_e32 v30, v13, v13
	v_mul_f32_e32 v32, v15, v15
	v_pk_add_f32 v[24:25], v[34:35], v[24:25]
	v_pk_add_f32 v[22:23], v[22:23], v[28:29]
	v_mul_f32_e32 v36, v1, v1
	v_mul_f32_e32 v37, v2, v2
	v_mul_f32_e32 v38, v3, v3
	v_pk_fma_f32 v[26:27], v[12:13], v[12:13], v[30:31] op_sel_hi:[1,1,0]
	v_pk_fma_f32 v[30:31], v[14:15], v[14:15], v[32:33] op_sel_hi:[1,1,0]
	v_pk_add_f32 v[24:25], v[24:25], v[24:25] op_sel:[0,1] op_sel_hi:[1,0]
	v_pk_add_f32 v[22:23], v[22:23], v[22:23] op_sel:[0,1] op_sel_hi:[1,0]
	v_mov_b32_e32 v27, v37
	v_mov_b32_e32 v31, v38
	v_mov_b32_e32 v25, v33
	v_mov_b32_e32 v23, v36
	v_pk_add_f32 v[26:27], v[26:27], v[30:31]
	v_pk_add_f32 v[22:23], v[24:25], v[22:23]
	s_nop 0
	v_pk_add_f32 v[22:23], v[22:23], v[26:27]
	s_nop 0
	v_add_f32_e32 v22, v22, v23
	ds_bpermute_b32 v23, v16, v22
	s_waitcnt lgkmcnt(0)
	v_add_f32_e32 v22, v22, v23
	ds_bpermute_b32 v23, v17, v22
	s_waitcnt lgkmcnt(0)
	v_add_f32_e32 v24, v22, v23
	ds_bpermute_b32 v25, v18, v24
	v_lshl_add_u64 v[22:23], v[68:69], 0, s[12:13]
	s_waitcnt lgkmcnt(0)
	v_add_f32_e32 v24, v24, v25
	ds_bpermute_b32 v25, v19, v24
	s_waitcnt lgkmcnt(0)
	v_add_f32_e32 v26, v24, v25
	ds_bpermute_b32 v27, v20, v26
	v_mov_b32_e32 v24, v8
	v_mov_b32_e32 v8, v4
	v_mov_b32_e32 v4, v12
	v_mov_b32_e32 v25, v10
	s_waitcnt lgkmcnt(0)
	v_add_f32_e32 v26, v26, v27
	ds_bpermute_b32 v27, v21, v26
	v_mov_b32_e32 v10, v9
	v_mov_b32_e32 v9, v6
	v_mov_b32_e32 v6, v5
	v_mov_b32_e32 v5, v14
	s_waitcnt lgkmcnt(0)
	v_add_f32_e32 v12, v26, v27
	v_fmamk_f32 v12, v12, 0x3a800000, v209
	v_mul_f32_e32 v14, 0x4f800000, v12
	v_cmp_gt_f32_e32 vcc, s47, v12
	v_mov_b32_e32 v26, v0
	v_mov_b32_e32 v27, v2
	v_cndmask_b32_e32 v12, v12, v14, vcc
	v_sqrt_f32_e32 v14, v12
	v_mov_b32_e32 v2, v1
	v_add_u32_e32 v0, -1, v14
	v_add_u32_e32 v1, 1, v14
	v_fma_f32 v28, -v0, v14, v12
	v_fma_f32 v29, -v1, v14, v12
	v_cmp_ge_f32_e64 s[12:13], 0, v28
	s_nop 1
	v_cndmask_b32_e64 v0, v14, v0, s[12:13]
	v_cmp_lt_f32_e64 s[12:13], 0, v29
	v_mov_b32_e32 v14, v13
	s_nop 0
	v_cndmask_b32_e64 v0, v0, v1, s[12:13]
	v_mul_f32_e32 v1, 0x37800000, v0
	v_cndmask_b32_e32 v0, v0, v1, vcc
	v_cmp_class_f32_e32 vcc, v12, v210
	s_nop 1
	v_cndmask_b32_e32 v0, v0, v12, vcc
	v_div_scale_f32 v1, s[12:13], v0, v0, 1.0
	v_rcp_f32_e32 v12, v1
	v_div_scale_f32 v13, vcc, 1.0, v0, 1.0
	v_fma_f32 v28, -v1, v12, 1.0
	v_fmac_f32_e32 v12, v28, v12
	v_mul_f32_e32 v28, v13, v12
	v_fma_f32 v29, -v1, v28, v13
	v_fmac_f32_e32 v28, v29, v12
	v_fma_f32 v1, -v1, v28, v13
	v_div_fmas_f32 v1, v1, v12, v28
	v_div_fixup_f32 v0, v1, v0, 1.0
	v_pk_mul_f32 v[10:11], v[10:11], v[0:1] op_sel_hi:[1,0]
	v_pk_mul_f32 v[12:13], v[24:25], v[0:1] op_sel_hi:[1,0]
	v_pk_mul_f32 v[8:9], v[8:9], v[0:1] op_sel_hi:[1,0]
	v_pk_mul_f32 v[6:7], v[6:7], v[0:1] op_sel_hi:[1,0]
	v_pk_mul_f32 v[4:5], v[4:5], v[0:1] op_sel_hi:[1,0]
	v_pk_mul_f32 v[14:15], v[14:15], v[0:1] op_sel_hi:[1,0]
	v_pk_mul_f32 v[24:25], v[26:27], v[0:1] op_sel_hi:[1,0]
	v_pk_mul_f32 v[0:1], v[2:3], v[0:1] op_sel_hi:[1,0]
	v_and_b32_sdwa v26, v11, v212 dst_sel:DWORD dst_unused:UNUSED_PAD src0_sel:WORD_1 src1_sel:DWORD
	v_and_b32_sdwa v27, v10, v212 dst_sel:DWORD dst_unused:UNUSED_PAD src0_sel:WORD_1 src1_sel:DWORD
	v_and_b32_sdwa v2, v13, v212 dst_sel:DWORD dst_unused:UNUSED_PAD src0_sel:WORD_1 src1_sel:DWORD
	v_and_b32_sdwa v3, v12, v212 dst_sel:DWORD dst_unused:UNUSED_PAD src0_sel:WORD_1 src1_sel:DWORD
	v_and_b32_sdwa v30, v7, v212 dst_sel:DWORD dst_unused:UNUSED_PAD src0_sel:WORD_1 src1_sel:DWORD
	v_and_b32_sdwa v31, v6, v212 dst_sel:DWORD dst_unused:UNUSED_PAD src0_sel:WORD_1 src1_sel:DWORD
	v_and_b32_sdwa v34, v15, v212 dst_sel:DWORD dst_unused:UNUSED_PAD src0_sel:WORD_1 src1_sel:DWORD
	v_and_b32_sdwa v35, v14, v212 dst_sel:DWORD dst_unused:UNUSED_PAD src0_sel:WORD_1 src1_sel:DWORD
	v_and_b32_sdwa v38, v1, v212 dst_sel:DWORD dst_unused:UNUSED_PAD src0_sel:WORD_1 src1_sel:DWORD
	v_and_b32_sdwa v39, v0, v212 dst_sel:DWORD dst_unused:UNUSED_PAD src0_sel:WORD_1 src1_sel:DWORD
	v_add3_u32 v11, v11, v26, s44
	v_add3_u32 v10, v10, v27, s44
	v_and_b32_sdwa v28, v9, v212 dst_sel:DWORD dst_unused:UNUSED_PAD src0_sel:WORD_1 src1_sel:DWORD
	v_and_b32_sdwa v29, v8, v212 dst_sel:DWORD dst_unused:UNUSED_PAD src0_sel:WORD_1 src1_sel:DWORD
	v_and_b32_sdwa v32, v5, v212 dst_sel:DWORD dst_unused:UNUSED_PAD src0_sel:WORD_1 src1_sel:DWORD
	v_and_b32_sdwa v33, v4, v212 dst_sel:DWORD dst_unused:UNUSED_PAD src0_sel:WORD_1 src1_sel:DWORD
	v_and_b32_sdwa v36, v25, v212 dst_sel:DWORD dst_unused:UNUSED_PAD src0_sel:WORD_1 src1_sel:DWORD
	v_and_b32_sdwa v37, v24, v212 dst_sel:DWORD dst_unused:UNUSED_PAD src0_sel:WORD_1 src1_sel:DWORD
	v_add3_u32 v3, v12, v3, s44
	v_add3_u32 v2, v13, v2, s44
	v_add3_u32 v7, v7, v30, s44
	v_add3_u32 v6, v6, v31, s44
	v_add3_u32 v12, v15, v34, s44
	v_add3_u32 v13, v14, v35, s44
	v_add3_u32 v1, v1, v38, s44
	v_add3_u32 v0, v0, v39, s44
	v_and_b32_e32 v11, 0xffff0000, v11
	v_and_b32_e32 v10, 0xffff0000, v10
	v_add3_u32 v8, v8, v29, s44
	v_add3_u32 v9, v9, v28, s44
	v_add3_u32 v4, v4, v33, s44
	v_add3_u32 v5, v5, v32, s44
	v_add3_u32 v14, v24, v37, s44
	v_add3_u32 v15, v25, v36, s44
	v_and_b32_e32 v7, 0xffff0000, v7
	v_and_b32_e32 v6, 0xffff0000, v6
	v_and_b32_e32 v12, 0xffff0000, v12
	v_and_b32_e32 v13, 0xffff0000, v13
	v_and_b32_e32 v24, 0xffff0000, v1
	v_and_b32_e32 v25, 0xffff0000, v0
	v_or_b32_sdwa v1, v11, v2 dst_sel:DWORD dst_unused:UNUSED_PAD src0_sel:DWORD src1_sel:WORD_1
	v_or_b32_sdwa v0, v10, v3 dst_sel:DWORD dst_unused:UNUSED_PAD src0_sel:DWORD src1_sel:WORD_1
	v_or_b32_sdwa v3, v7, v9 dst_sel:DWORD dst_unused:UNUSED_PAD src0_sel:DWORD src1_sel:WORD_1
	v_or_b32_sdwa v2, v6, v8 dst_sel:DWORD dst_unused:UNUSED_PAD src0_sel:DWORD src1_sel:WORD_1
	v_or_b32_sdwa v5, v12, v5 dst_sel:DWORD dst_unused:UNUSED_PAD src0_sel:DWORD src1_sel:WORD_1
	v_or_b32_sdwa v4, v13, v4 dst_sel:DWORD dst_unused:UNUSED_PAD src0_sel:DWORD src1_sel:WORD_1
	v_or_b32_sdwa v7, v24, v15 dst_sel:DWORD dst_unused:UNUSED_PAD src0_sel:DWORD src1_sel:WORD_1
	v_or_b32_sdwa v6, v25, v14 dst_sel:DWORD dst_unused:UNUSED_PAD src0_sel:DWORD src1_sel:WORD_1
	global_store_dwordx2 v[22:23], v[0:1], off
	global_store_dwordx2 v[22:23], v[2:3], off offset:512
	global_store_dwordx2 v[22:23], v[4:5], off offset:1024
	global_store_dwordx2 v[22:23], v[6:7], off offset:1536
	s_cbranch_scc1 .LBB0_241
.LBB0_239:
	s_mov_b32 s58, s57
	s_add_i32 s56, s68, s92
	s_cmpk_lt_i32 s56, 0x4000
	s_cselect_b64 s[52:53], -1, 0
	s_cselect_b32 s57, 1, 0
	s_mov_b64 s[12:13], s[68:69]
	s_mov_b64 s[70:71], s[66:67]
	s_cmp_eq_u32 s58, 1
	s_cbranch_scc1 .Lpp_have
	s_cmpk_lt_i32 s68, 0x4000
	s_cbranch_scc1 .LBB0_238
	s_add_i32 s4, s68, 0xffffc000
	v_readlane_b32 s16, v254, 3
	s_lshl_b64 s[12:13], s[4:5], 12
	v_readlane_b32 s18, v254, 5
	v_readlane_b32 s19, v254, 6
	s_add_u32 s70, s18, s12
	s_mov_b32 s4, s68
	s_addc_u32 s71, s19, s13
	s_mov_b64 s[12:13], s[4:5]
	v_readlane_b32 s17, v254, 4
	v_readlane_b32 s20, v254, 7
	v_readlane_b32 s21, v254, 8
	v_readlane_b32 s22, v254, 9
	v_readlane_b32 s23, v254, 10
	v_readlane_b32 s24, v254, 11
	v_readlane_b32 s25, v254, 12
	v_readlane_b32 s26, v254, 13
	v_readlane_b32 s27, v254, 14
	v_readlane_b32 s28, v254, 15
	v_readlane_b32 s29, v254, 16
	v_readlane_b32 s30, v254, 17
	v_readlane_b32 s31, v254, 18
	s_branch .LBB0_238
.Lpp_have:
	s_waitcnt vmcnt(4)
	v_mov_b64_e32 v[8:9], v[220:221]
	v_mov_b64_e32 v[10:11], v[222:223]
	v_mov_b64_e32 v[4:5], v[224:225]
	v_mov_b64_e32 v[6:7], v[226:227]
	v_mov_b64_e32 v[0:1], v[228:229]
	v_mov_b64_e32 v[2:3], v[230:231]
	v_mov_b64_e32 v[12:13], v[232:233]
	v_mov_b64_e32 v[14:15], v[234:235]
	s_lshl_b64 s[12:13], s[12:13], 11
	s_add_u32 s68, s68, s92
	s_addc_u32 s69, s69, s93
	s_add_u32 s66, s66, s42
	s_addc_u32 s67, s67, s43
	s_cmpk_gt_i32 s68, 0x41ff
	s_mov_b64 exec, s[52:53]
	global_load_dwordx4 v[220:223], v189, s[66:67]
	global_load_dwordx4 v[224:227], v189, s[66:67] offset:1024
	global_load_dwordx4 v[228:231], v189, s[66:67] offset:3072
	global_load_dwordx4 v[232:235], v189, s[66:67] offset:2048
	s_mov_b64 exec, -1
	v_pk_mul_f32 v[22:23], v[10:11], v[10:11]
	v_pk_mul_f32 v[24:25], v[8:9], v[8:9]
	v_pk_mul_f32 v[26:27], v[6:7], v[6:7]
	v_pk_mul_f32 v[28:29], v[4:5], v[4:5]
	v_pk_mov_b32 v[34:35], v[24:25], v[22:23] op_sel:[1,0]
	v_mov_b32_e32 v25, v23
	v_pk_mov_b32 v[22:23], v[28:29], v[26:27] op_sel:[1,0]
	v_mov_b32_e32 v29, v27
	v_mul_f32_e32 v33, v0, v0
	v_mul_f32_e32 v30, v13, v13
	v_mul_f32_e32 v32, v15, v15
	v_pk_add_f32 v[24:25], v[34:35], v[24:25]
	v_pk_add_f32 v[22:23], v[22:23], v[28:29]
	v_mul_f32_e32 v36, v1, v1
	v_mul_f32_e32 v37, v2, v2
	v_mul_f32_e32 v38, v3, v3
	v_pk_fma_f32 v[26:27], v[12:13], v[12:13], v[30:31] op_sel_hi:[1,1,0]
	v_pk_fma_f32 v[30:31], v[14:15], v[14:15], v[32:33] op_sel_hi:[1,1,0]
	v_pk_add_f32 v[24:25], v[24:25], v[24:25] op_sel:[0,1] op_sel_hi:[1,0]
	v_pk_add_f32 v[22:23], v[22:23], v[22:23] op_sel:[0,1] op_sel_hi:[1,0]
	v_mov_b32_e32 v27, v37
	v_mov_b32_e32 v31, v38
	v_mov_b32_e32 v25, v33
	v_mov_b32_e32 v23, v36
	v_pk_add_f32 v[26:27], v[26:27], v[30:31]
	v_pk_add_f32 v[22:23], v[24:25], v[22:23]
	s_nop 0
	v_pk_add_f32 v[22:23], v[22:23], v[26:27]
	s_nop 0
	v_add_f32_e32 v22, v22, v23
	ds_bpermute_b32 v23, v16, v22
	s_waitcnt lgkmcnt(0)
	v_add_f32_e32 v22, v22, v23
	ds_bpermute_b32 v23, v17, v22
	s_waitcnt lgkmcnt(0)
	v_add_f32_e32 v24, v22, v23
	ds_bpermute_b32 v25, v18, v24
	v_lshl_add_u64 v[22:23], v[68:69], 0, s[12:13]
	s_waitcnt lgkmcnt(0)
	v_add_f32_e32 v24, v24, v25
	ds_bpermute_b32 v25, v19, v24
	s_waitcnt lgkmcnt(0)
	v_add_f32_e32 v26, v24, v25
	ds_bpermute_b32 v27, v20, v26
	v_mov_b32_e32 v24, v8
	v_mov_b32_e32 v8, v4
	v_mov_b32_e32 v4, v12
	v_mov_b32_e32 v25, v10
	s_waitcnt lgkmcnt(0)
	v_add_f32_e32 v26, v26, v27
	ds_bpermute_b32 v27, v21, v26
	v_mov_b32_e32 v10, v9
	v_mov_b32_e32 v9, v6
	v_mov_b32_e32 v6, v5
	v_mov_b32_e32 v5, v14
	s_waitcnt lgkmcnt(0)
	v_add_f32_e32 v12, v26, v27
	v_fmamk_f32 v12, v12, 0x3a800000, v209
	v_mul_f32_e32 v14, 0x4f800000, v12
	v_cmp_gt_f32_e32 vcc, s47, v12
	v_mov_b32_e32 v26, v0
	v_mov_b32_e32 v27, v2
	v_cndmask_b32_e32 v12, v12, v14, vcc
	v_sqrt_f32_e32 v14, v12
	v_mov_b32_e32 v2, v1
	v_add_u32_e32 v0, -1, v14
	v_add_u32_e32 v1, 1, v14
	v_fma_f32 v28, -v0, v14, v12
	v_fma_f32 v29, -v1, v14, v12
	v_cmp_ge_f32_e64 s[12:13], 0, v28
	s_nop 1
	v_cndmask_b32_e64 v0, v14, v0, s[12:13]
	v_cmp_lt_f32_e64 s[12:13], 0, v29
	v_mov_b32_e32 v14, v13
	s_nop 0
	v_cndmask_b32_e64 v0, v0, v1, s[12:13]
	v_mul_f32_e32 v1, 0x37800000, v0
	v_cndmask_b32_e32 v0, v0, v1, vcc
	v_cmp_class_f32_e32 vcc, v12, v210
	s_nop 1
	v_cndmask_b32_e32 v0, v0, v12, vcc
	v_div_scale_f32 v1, s[12:13], v0, v0, 1.0
	v_rcp_f32_e32 v12, v1
	v_div_scale_f32 v13, vcc, 1.0, v0, 1.0
	v_fma_f32 v28, -v1, v12, 1.0
	v_fmac_f32_e32 v12, v28, v12
	v_mul_f32_e32 v28, v13, v12
	v_fma_f32 v29, -v1, v28, v13
	v_fmac_f32_e32 v28, v29, v12
	v_fma_f32 v1, -v1, v28, v13
	v_div_fmas_f32 v1, v1, v12, v28
	v_div_fixup_f32 v0, v1, v0, 1.0
	v_pk_mul_f32 v[10:11], v[10:11], v[0:1] op_sel_hi:[1,0]
	v_pk_mul_f32 v[12:13], v[24:25], v[0:1] op_sel_hi:[1,0]
	v_pk_mul_f32 v[8:9], v[8:9], v[0:1] op_sel_hi:[1,0]
	v_pk_mul_f32 v[6:7], v[6:7], v[0:1] op_sel_hi:[1,0]
	v_pk_mul_f32 v[4:5], v[4:5], v[0:1] op_sel_hi:[1,0]
	v_pk_mul_f32 v[14:15], v[14:15], v[0:1] op_sel_hi:[1,0]
	v_pk_mul_f32 v[24:25], v[26:27], v[0:1] op_sel_hi:[1,0]
	v_pk_mul_f32 v[0:1], v[2:3], v[0:1] op_sel_hi:[1,0]
	v_and_b32_sdwa v26, v11, v212 dst_sel:DWORD dst_unused:UNUSED_PAD src0_sel:WORD_1 src1_sel:DWORD
	v_and_b32_sdwa v27, v10, v212 dst_sel:DWORD dst_unused:UNUSED_PAD src0_sel:WORD_1 src1_sel:DWORD
	v_and_b32_sdwa v2, v13, v212 dst_sel:DWORD dst_unused:UNUSED_PAD src0_sel:WORD_1 src1_sel:DWORD
	v_and_b32_sdwa v3, v12, v212 dst_sel:DWORD dst_unused:UNUSED_PAD src0_sel:WORD_1 src1_sel:DWORD
	v_and_b32_sdwa v30, v7, v212 dst_sel:DWORD dst_unused:UNUSED_PAD src0_sel:WORD_1 src1_sel:DWORD
	v_and_b32_sdwa v31, v6, v212 dst_sel:DWORD dst_unused:UNUSED_PAD src0_sel:WORD_1 src1_sel:DWORD
	v_and_b32_sdwa v34, v15, v212 dst_sel:DWORD dst_unused:UNUSED_PAD src0_sel:WORD_1 src1_sel:DWORD
	v_and_b32_sdwa v35, v14, v212 dst_sel:DWORD dst_unused:UNUSED_PAD src0_sel:WORD_1 src1_sel:DWORD
	v_and_b32_sdwa v38, v1, v212 dst_sel:DWORD dst_unused:UNUSED_PAD src0_sel:WORD_1 src1_sel:DWORD
	v_and_b32_sdwa v39, v0, v212 dst_sel:DWORD dst_unused:UNUSED_PAD src0_sel:WORD_1 src1_sel:DWORD
	v_add3_u32 v11, v11, v26, s44
	v_add3_u32 v10, v10, v27, s44
	v_and_b32_sdwa v28, v9, v212 dst_sel:DWORD dst_unused:UNUSED_PAD src0_sel:WORD_1 src1_sel:DWORD
	v_and_b32_sdwa v29, v8, v212 dst_sel:DWORD dst_unused:UNUSED_PAD src0_sel:WORD_1 src1_sel:DWORD
	v_and_b32_sdwa v32, v5, v212 dst_sel:DWORD dst_unused:UNUSED_PAD src0_sel:WORD_1 src1_sel:DWORD
	v_and_b32_sdwa v33, v4, v212 dst_sel:DWORD dst_unused:UNUSED_PAD src0_sel:WORD_1 src1_sel:DWORD
	v_and_b32_sdwa v36, v25, v212 dst_sel:DWORD dst_unused:UNUSED_PAD src0_sel:WORD_1 src1_sel:DWORD
	v_and_b32_sdwa v37, v24, v212 dst_sel:DWORD dst_unused:UNUSED_PAD src0_sel:WORD_1 src1_sel:DWORD
	v_add3_u32 v3, v12, v3, s44
	v_add3_u32 v2, v13, v2, s44
	v_add3_u32 v7, v7, v30, s44
	v_add3_u32 v6, v6, v31, s44
	v_add3_u32 v12, v15, v34, s44
	v_add3_u32 v13, v14, v35, s44
	v_add3_u32 v1, v1, v38, s44
	v_add3_u32 v0, v0, v39, s44
	v_and_b32_e32 v11, 0xffff0000, v11
	v_and_b32_e32 v10, 0xffff0000, v10
	v_add3_u32 v8, v8, v29, s44
	v_add3_u32 v9, v9, v28, s44
	v_add3_u32 v4, v4, v33, s44
	v_add3_u32 v5, v5, v32, s44
	v_add3_u32 v14, v24, v37, s44
	v_add3_u32 v15, v25, v36, s44
	v_and_b32_e32 v7, 0xffff0000, v7
	v_and_b32_e32 v6, 0xffff0000, v6
	v_and_b32_e32 v12, 0xffff0000, v12
	v_and_b32_e32 v13, 0xffff0000, v13
	v_and_b32_e32 v24, 0xffff0000, v1
	v_and_b32_e32 v25, 0xffff0000, v0
	v_or_b32_sdwa v1, v11, v2 dst_sel:DWORD dst_unused:UNUSED_PAD src0_sel:DWORD src1_sel:WORD_1
	v_or_b32_sdwa v0, v10, v3 dst_sel:DWORD dst_unused:UNUSED_PAD src0_sel:DWORD src1_sel:WORD_1
	v_or_b32_sdwa v3, v7, v9 dst_sel:DWORD dst_unused:UNUSED_PAD src0_sel:DWORD src1_sel:WORD_1
	v_or_b32_sdwa v2, v6, v8 dst_sel:DWORD dst_unused:UNUSED_PAD src0_sel:DWORD src1_sel:WORD_1
	v_or_b32_sdwa v5, v12, v5 dst_sel:DWORD dst_unused:UNUSED_PAD src0_sel:DWORD src1_sel:WORD_1
	v_or_b32_sdwa v4, v13, v4 dst_sel:DWORD dst_unused:UNUSED_PAD src0_sel:DWORD src1_sel:WORD_1
	v_or_b32_sdwa v7, v24, v15 dst_sel:DWORD dst_unused:UNUSED_PAD src0_sel:DWORD src1_sel:WORD_1
	v_or_b32_sdwa v6, v25, v14 dst_sel:DWORD dst_unused:UNUSED_PAD src0_sel:DWORD src1_sel:WORD_1
	global_store_dwordx2 v[22:23], v[0:1], off
	global_store_dwordx2 v[22:23], v[2:3], off offset:512
	global_store_dwordx2 v[22:23], v[4:5], off offset:1024
	global_store_dwordx2 v[22:23], v[6:7], off offset:1536
	s_cbranch_scc1 .LBB0_241
	s_branch .LBB0_239
